# all sample-row small GEMM units (P3 x2, P4, P5, P6): fragment loads issued in one deep batch instead of a 3-4 deep drip
# speedup vs baseline: 1.0115x; 1.0044x over previous
; #define LAS __attribute__((address_space(3)))
; __device__ __forceinline__ unsigned f2bf(float f) { unsigned u = __builtin_bit_cast(unsigned, f); return (u + 0x7fffu + ((u >> 16) & 1u)) >> 16; }
; __device__ __forceinline__ int crow(int r, int hi) { return (r & 3) + 8 * (r >> 2) + 4 * hi; }
; #define MFMA32(a, b, c) __builtin_amdgcn_mfma_f32_32x32x16_bf16((a), (b), (c), 0, 0, 0)
; template <int NB, class F> __device__ __forceinline__ void small_gemm(const bf16* A, int K, const bf16* const (&Bs)[NB], int rg, int wave_s, LAS unsigned char* lds, const F& epi) {
;     ...
;     for (int s0 = 0; s0 < steps; s0 += 8) {
;         bf16x8 af[8], bfr[NB][8];
; #pragma unroll
;         for (int s = 0; s < 8; ++s) if (s0 + s < steps) { af[s] = *(const bf16x8*)(ap + 16 * (s0 + s));
; #pragma unroll
;             for (int nb = 0; nb < NB; ++nb) bfr[nb][s] = *(const bf16x8*)(bp[nb] + 16 * (s0 + s)); }
; #pragma unroll
;         for (int s = 0; s < 8; ++s) if (s0 + s < steps) {
; #pragma unroll
;             for (int nb = 0; nb < NB; ++nb) acc[nb] = MFMA32(af[s], bfr[nb][s], acc[nb]); }
;     }
;     LAS float* P = (LAS float*)lds;
; #pragma unroll
;     for (int nb = 0; nb < NB; ++nb)
; #pragma unroll
;         for (int i = 0; i < 16; ++i) P[((w * NB + nb) * 16 + i) * 64 + lane] = acc[nb][i];
;     __syncthreads();
;     float v[NB][2];
; #pragma unroll
;     for (int nb = 0; nb < NB; ++nb)
; #pragma unroll
;         for (int ii = 0; ii < 2; ++ii) { float t = 0.f;
; #pragma unroll
;             for (int ww = 0; ww < 8; ++ww) t += P[((ww * NB + nb) * 16 + 2 * w + ii) * 64 + lane];
;             v[nb][ii] = t; }
;     epi(v, w, r32, hi);
; __global__ void __launch_bounds__(512, 2) hybrid_fwd(Ctx c) {
;     ...
;         small_gemm<1>((const bf16*)(ws + WS_VR), D, Bs, rg, wave0, lds, [&](const float (&v)[1][2], int w, int r32, int hi) {
;             const int col = 32 * cg + r32;
; #pragma unroll
;             for (int ii = 0; ii < 2; ++ii) { const int row = ROW_S0 + 32 * rg + crow(2 * w + ii, hi);
;                 MG[(size_t)row * D + col] = (bf16)f2bf(bf2f(gate_row(c, 0, row)[col]) * v[0][ii]); } });
.LBB0_1008:
	s_mov_b32 s24, -1
	s_and_b32 s22, s13, 0xffffffe0
	v_mbcnt_lo_u32_b32 v0, s24, 0
	v_mbcnt_hi_u32_b32 v0, s24, v0
	s_and_b32 s25, s17, 0xe0
	s_waitcnt vmcnt(0)
	v_add_u32_e32 v56, s33, v0
	s_ashr_i32 s23, s22, 31
	s_or_b32 s21, s25, 0x8000
	s_lshl_b64 s[22:23], s[22:23], 11
	v_and_b32_e32 v2, 31, v56
	v_or_b32_e32 v0, s21, v2
	s_add_u32 s22, s8, s22
	v_bfe_u32 v57, v56, 5, 1
	v_lshlrev_b32_e32 v16, 11, v0
	s_addc_u32 s23, s9, s23
	v_lshl_add_u64 v[0:1], s[0:1], 0, v[16:17]
	v_lshlrev_b32_e32 v16, 4, v57
	v_lshl_add_u64 v[8:9], v[0:1], 0, v[16:17]
	v_lshl_add_u64 v[0:1], s[22:23], 0, v[16:17]
	v_lshlrev_b32_e32 v16, 11, v2
	v_lshl_add_u64 v[54:55], v[0:1], 0, v[16:17]
	global_load_dwordx4 v[64:67], v[8:9], off
	global_load_dwordx4 v[68:71], v[54:55], off
	global_load_dwordx4 v[72:75], v[8:9], off offset:32
	global_load_dwordx4 v[76:79], v[54:55], off offset:32
	global_load_dwordx4 v[80:83], v[8:9], off offset:64
	global_load_dwordx4 v[84:87], v[54:55], off offset:64
	global_load_dwordx4 v[88:91], v[8:9], off offset:96
	global_load_dwordx4 v[92:95], v[54:55], off offset:96
	global_load_dwordx4 v[96:99], v[8:9], off offset:128
	global_load_dwordx4 v[100:103], v[54:55], off offset:128
	global_load_dwordx4 v[104:107], v[8:9], off offset:160
	global_load_dwordx4 v[108:111], v[54:55], off offset:160
	global_load_dwordx4 v[112:115], v[8:9], off offset:192
	global_load_dwordx4 v[116:119], v[54:55], off offset:192
	global_load_dwordx4 v[120:123], v[8:9], off offset:224
	global_load_dwordx4 v[124:127], v[54:55], off offset:224
	v_and_b32_e32 v16, 63, v56
	s_add_i32 s20, s20, s15
	s_add_i32 s17, s17, s18
	s_waitcnt vmcnt(14)
	v_mfma_f32_32x32x16_bf16 v[0:15], v[64:67], v[68:71], 0
	s_waitcnt vmcnt(12)
	v_mfma_f32_32x32x16_bf16 v[0:15], v[72:75], v[76:79], v[0:15]
	s_waitcnt vmcnt(10)
	v_mfma_f32_32x32x16_bf16 v[0:15], v[80:83], v[84:87], v[0:15]
	s_waitcnt vmcnt(8)
	v_mfma_f32_32x32x16_bf16 v[0:15], v[88:91], v[92:95], v[0:15]
	s_waitcnt vmcnt(6)
	v_mfma_f32_32x32x16_bf16 v[0:15], v[96:99], v[100:103], v[0:15]
	s_waitcnt vmcnt(4)
	v_mfma_f32_32x32x16_bf16 v[0:15], v[104:107], v[108:111], v[0:15]
	s_waitcnt vmcnt(2)
	v_mfma_f32_32x32x16_bf16 v[0:15], v[112:115], v[116:119], v[0:15]
	s_waitcnt vmcnt(0)
	v_mfma_f32_32x32x16_bf16 v[0:15], v[120:123], v[124:127], v[0:15]
	v_lshl_or_b32 v29, v57, 2, s12
	v_bfi_b32 v26, 31, v56, s13
	v_lshl_add_u32 v28, v16, 2, 0
	v_add_u32_e32 v16, s25, v29
	v_ashrrev_i32_e32 v27, 31, v26
	s_add_i32 s13, s13, s16
	v_add_u32_e32 v30, s10, v28
	s_cmpk_gt_i32 s20, 0xff
	v_lshlrev_b64 v[24:25], 11, v[16:17]
	v_lshlrev_b64 v[22:23], 1, v[26:27]
	v_lshl_add_u64 v[24:25], s[2:3], 0, v[24:25]
	v_lshl_add_u64 v[24:25], v[24:25], 0, v[22:23]
	v_or_b32_e32 v26, 1, v29
	v_add_u32_e32 v16, s25, v26
	s_nop 11
	ds_write2st64_b32 v30, v0, v1 offset1:1
	ds_write2st64_b32 v30, v2, v3 offset0:2 offset1:3
	ds_write2st64_b32 v30, v4, v5 offset0:4 offset1:5
	ds_write2st64_b32 v30, v6, v7 offset0:6 offset1:7
	ds_write2st64_b32 v30, v8, v9 offset0:8 offset1:9
	ds_write2st64_b32 v30, v10, v11 offset0:10 offset1:11
	ds_write2st64_b32 v30, v12, v13 offset0:12 offset1:13
	ds_write2st64_b32 v30, v14, v15 offset0:14 offset1:15
	s_waitcnt lgkmcnt(0)
	s_barrier
	global_load_ushort v24, v[24:25], off
	v_lshlrev_b64 v[4:5], 11, v[16:17]
	v_add_u32_e32 v25, s11, v28
	v_lshl_add_u64 v[4:5], s[2:3], 0, v[4:5]
	v_lshl_add_u64 v[2:3], s[6:7], 0, v[22:23]
	v_lshl_add_u64 v[4:5], v[4:5], 0, v[22:23]
	ds_read2st64_b32 v[6:7], v25 offset1:1
	ds_read2st64_b32 v[8:9], v25 offset0:16 offset1:17
	ds_read2st64_b32 v[10:11], v25 offset0:32 offset1:33
	ds_read2st64_b32 v[12:13], v25 offset0:48 offset1:49
	ds_read2st64_b32 v[14:15], v25 offset0:64 offset1:65
	ds_read2st64_b32 v[18:19], v25 offset0:80 offset1:81
	ds_read2st64_b32 v[20:21], v25 offset0:96 offset1:97
	ds_read2st64_b32 v[22:23], v25 offset0:112 offset1:113
	s_waitcnt lgkmcnt(7)
	v_add_f32_e32 v6, 0, v6
	s_waitcnt lgkmcnt(6)
	v_add_f32_e32 v6, v6, v8
	s_waitcnt lgkmcnt(5)
	v_add_f32_e32 v6, v6, v10
	s_waitcnt lgkmcnt(4)
	v_add_f32_e32 v6, v6, v12
	s_waitcnt lgkmcnt(3)
	v_add_f32_e32 v6, v6, v14
	s_waitcnt lgkmcnt(2)
	v_add_f32_e32 v6, v6, v18
	s_waitcnt lgkmcnt(1)
	v_add_f32_e32 v6, v6, v20
	s_waitcnt lgkmcnt(0)
	v_add_f32_e32 v6, v6, v22
	v_mov_b32_e32 v1, v17
	v_add_u32_e32 v0, s21, v29
	v_lshlrev_b64 v[0:1], 11, v[0:1]
	v_lshl_add_u64 v[0:1], v[2:3], 0, v[0:1]
	s_waitcnt vmcnt(0)
	v_lshlrev_b32_e32 v8, 16, v24
	v_mul_f32_e32 v6, v6, v8
	v_bfe_u32 v8, v6, 16, 1
	v_add3_u32 v6, v6, v8, s19
	global_store_short_d16_hi v[0:1], v6, off
	global_load_ushort v4, v[4:5], off
	v_mov_b32_e32 v1, v17
	v_add_u32_e32 v0, s21, v26
	v_lshlrev_b64 v[0:1], 11, v[0:1]
	v_lshl_add_u64 v[0:1], v[2:3], 0, v[0:1]
	v_add_f32_e32 v2, 0, v7
	v_add_f32_e32 v2, v2, v9
	v_add_f32_e32 v2, v2, v11
	v_add_f32_e32 v2, v2, v13
	v_add_f32_e32 v2, v2, v15
	v_add_f32_e32 v2, v2, v19
	v_add_f32_e32 v2, v2, v21
	v_add_f32_e32 v2, v2, v23
	s_waitcnt vmcnt(0)
	v_lshlrev_b32_e32 v3, 16, v4
	v_mul_f32_e32 v2, v2, v3
	v_bfe_u32 v3, v2, 16, 1
	v_add3_u32 v2, v2, v3, s19
	global_store_short_d16_hi v[0:1], v2, off
	s_barrier
	s_cbranch_scc0 .LBB0_1008

; #define LAS __attribute__((address_space(3)))
; __device__ __forceinline__ unsigned f2bf(float f) { unsigned u = __builtin_bit_cast(unsigned, f); return (u + 0x7fffu + ((u >> 16) & 1u)) >> 16; }
; __device__ __forceinline__ int crow(int r, int hi) { return (r & 3) + 8 * (r >> 2) + 4 * hi; }
; #define MFMA32(a, b, c) __builtin_amdgcn_mfma_f32_32x32x16_bf16((a), (b), (c), 0, 0, 0)
; template <int NB, class F> __device__ __forceinline__ void small_gemm(const bf16* A, int K, const bf16* const (&Bs)[NB], int rg, int wave_s, LAS unsigned char* lds, const F& epi) {
;     ...
;     for (int s0 = 0; s0 < steps; s0 += 8) {
;         bf16x8 af[8], bfr[NB][8];
; #pragma unroll
;         for (int s = 0; s < 8; ++s) if (s0 + s < steps) { af[s] = *(const bf16x8*)(ap + 16 * (s0 + s));
; #pragma unroll
;             for (int nb = 0; nb < NB; ++nb) bfr[nb][s] = *(const bf16x8*)(bp[nb] + 16 * (s0 + s)); }
; #pragma unroll
;         for (int s = 0; s < 8; ++s) if (s0 + s < steps) {
; #pragma unroll
;             for (int nb = 0; nb < NB; ++nb) acc[nb] = MFMA32(af[s], bfr[nb][s], acc[nb]); }
;     }
;     LAS float* P = (LAS float*)lds;
; #pragma unroll
;     for (int nb = 0; nb < NB; ++nb)
; #pragma unroll
;         for (int i = 0; i < 16; ++i) P[((w * NB + nb) * 16 + i) * 64 + lane] = acc[nb][i];
;     __syncthreads();
;     float v[NB][2];
; #pragma unroll
;     for (int nb = 0; nb < NB; ++nb)
; #pragma unroll
;         for (int ii = 0; ii < 2; ++ii) { float t = 0.f;
; #pragma unroll
;             for (int ww = 0; ww < 8; ++ww) t += P[((ww * NB + nb) * 16 + 2 * w + ii) * 64 + lane];
;             v[nb][ii] = t; }
;     epi(v, w, r32, hi);
; __global__ void __launch_bounds__(512, 2) hybrid_fwd(Ctx c) {
;     ...
;         small_gemm<1>((const bf16*)(ws + WS_YD), D, Bs, rg, wave0, lds, [&](const float (&v)[1][2], int w, int r32, int hi) {
;             const int col = 32 * cg + r32;
; #pragma unroll
;             for (int ii = 0; ii < 2; ++ii) { const int row = ROW_S0 + 32 * rg + crow(2 * w + ii, hi); const size_t idx = (size_t)row * D + col;
;                 MG[idx] = (bf16)f2bf(bf2f(MG[idx]) + bf2f(gate_row(c, 1, row)[col]) * v[0][ii]); } });
.LBB0_1035:
	s_mov_b32 s21, -1
	s_and_b32 s22, s13, 0xffffffe0
	v_mbcnt_lo_u32_b32 v0, s21, 0
	v_mbcnt_hi_u32_b32 v0, s21, v0
	s_and_b32 s24, s17, 0xe0
	s_waitcnt vmcnt(2)
	v_add_u32_e32 v60, s33, v0
	s_ashr_i32 s23, s22, 31
	s_or_b32 s25, s24, 0x8000
	s_lshl_b64 s[22:23], s[22:23], 11
	v_and_b32_e32 v2, 31, v60
	v_or_b32_e32 v0, s25, v2
	s_add_u32 s22, s8, s22
	v_bfe_u32 v61, v60, 5, 1
	v_lshlrev_b32_e32 v16, 11, v0
	s_addc_u32 s23, s9, s23
	v_lshl_add_u64 v[0:1], s[0:1], 0, v[16:17]
	v_lshlrev_b32_e32 v16, 4, v61
	v_lshl_add_u64 v[8:9], v[0:1], 0, v[16:17]
	v_lshl_add_u64 v[0:1], s[22:23], 0, v[16:17]
	v_lshlrev_b32_e32 v16, 11, v2
	v_lshl_add_u64 v[58:59], v[0:1], 0, v[16:17]
	global_load_dwordx4 v[64:67], v[8:9], off
	global_load_dwordx4 v[68:71], v[58:59], off
	global_load_dwordx4 v[72:75], v[8:9], off offset:32
	global_load_dwordx4 v[76:79], v[58:59], off offset:32
	global_load_dwordx4 v[80:83], v[8:9], off offset:64
	global_load_dwordx4 v[84:87], v[58:59], off offset:64
	global_load_dwordx4 v[88:91], v[8:9], off offset:96
	global_load_dwordx4 v[92:95], v[58:59], off offset:96
	global_load_dwordx4 v[96:99], v[8:9], off offset:128
	global_load_dwordx4 v[100:103], v[58:59], off offset:128
	global_load_dwordx4 v[104:107], v[8:9], off offset:160
	global_load_dwordx4 v[108:111], v[58:59], off offset:160
	global_load_dwordx4 v[112:115], v[8:9], off offset:192
	global_load_dwordx4 v[116:119], v[58:59], off offset:192
	global_load_dwordx4 v[120:123], v[8:9], off offset:224
	global_load_dwordx4 v[124:127], v[58:59], off offset:224
	v_and_b32_e32 v16, 63, v60
	s_add_i32 s20, s20, s15
	s_add_i32 s17, s17, s18
	s_waitcnt vmcnt(14)
	v_mfma_f32_32x32x16_bf16 v[0:15], v[64:67], v[68:71], 0
	s_waitcnt vmcnt(12)
	v_mfma_f32_32x32x16_bf16 v[0:15], v[72:75], v[76:79], v[0:15]
	s_waitcnt vmcnt(10)
	v_mfma_f32_32x32x16_bf16 v[0:15], v[80:83], v[84:87], v[0:15]
	s_waitcnt vmcnt(8)
	v_mfma_f32_32x32x16_bf16 v[0:15], v[88:91], v[92:95], v[0:15]
	s_waitcnt vmcnt(6)
	v_mfma_f32_32x32x16_bf16 v[0:15], v[96:99], v[100:103], v[0:15]
	s_waitcnt vmcnt(4)
	v_mfma_f32_32x32x16_bf16 v[0:15], v[104:107], v[108:111], v[0:15]
	s_waitcnt vmcnt(2)
	v_mfma_f32_32x32x16_bf16 v[0:15], v[112:115], v[116:119], v[0:15]
	s_waitcnt vmcnt(0)
	v_mfma_f32_32x32x16_bf16 v[0:15], v[120:123], v[124:127], v[0:15]
	v_lshl_or_b32 v31, v61, 2, s12
	v_lshl_add_u32 v30, v16, 2, 0
	v_add_u32_e32 v16, s25, v31
	v_add_u32_e32 v32, s10, v30
	v_bfi_b32 v22, 31, v60, s13
	v_ashrrev_i32_e32 v23, 31, v22
	v_lshlrev_b64 v[22:23], 1, v[22:23]
	v_lshl_add_u64 v[24:25], s[6:7], 0, v[22:23]
	s_add_i32 s13, s13, s16
	s_cmpk_gt_i32 s20, 0xff
	v_lshlrev_b64 v[26:27], 11, v[16:17]
	v_add_u32_e32 v16, s24, v31
	v_lshlrev_b64 v[28:29], 11, v[16:17]
	v_lshl_add_u64 v[26:27], v[24:25], 0, v[26:27]
	v_lshl_add_u64 v[28:29], s[4:5], 0, v[28:29]
	v_lshl_add_u64 v[28:29], v[28:29], 0, v[22:23]
	s_nop 11
	ds_write2st64_b32 v32, v0, v1 offset1:1
	ds_write2st64_b32 v32, v2, v3 offset0:2 offset1:3
	ds_write2st64_b32 v32, v4, v5 offset0:4 offset1:5
	ds_write2st64_b32 v32, v6, v7 offset0:6 offset1:7
	ds_write2st64_b32 v32, v8, v9 offset0:8 offset1:9
	ds_write2st64_b32 v32, v10, v11 offset0:10 offset1:11
	ds_write2st64_b32 v32, v12, v13 offset0:12 offset1:13
	ds_write2st64_b32 v32, v14, v15 offset0:14 offset1:15
	s_waitcnt lgkmcnt(0)
	s_barrier
	global_load_ushort v32, v[26:27], off
	global_load_ushort v33, v[28:29], off
	v_add_u32_e32 v20, s11, v30
	ds_read2st64_b32 v[4:5], v20 offset1:1
	ds_read2st64_b32 v[6:7], v20 offset0:16 offset1:17
	ds_read2st64_b32 v[8:9], v20 offset0:32 offset1:33
	ds_read2st64_b32 v[10:11], v20 offset0:48 offset1:49
	ds_read2st64_b32 v[12:13], v20 offset0:64 offset1:65
	ds_read2st64_b32 v[14:15], v20 offset0:80 offset1:81
	ds_read2st64_b32 v[18:19], v20 offset0:96 offset1:97
	ds_read2st64_b32 v[20:21], v20 offset0:112 offset1:113
	s_waitcnt lgkmcnt(7)
	v_add_f32_e32 v4, 0, v4
	s_waitcnt lgkmcnt(6)
	v_add_f32_e32 v4, v4, v6
	s_waitcnt lgkmcnt(5)
	v_add_f32_e32 v4, v4, v8
	s_waitcnt lgkmcnt(4)
	v_add_f32_e32 v4, v4, v10
	s_waitcnt lgkmcnt(3)
	v_add_f32_e32 v4, v4, v12
	s_waitcnt lgkmcnt(2)
	v_add_f32_e32 v4, v4, v14
	v_or_b32_e32 v2, 1, v31
	s_waitcnt lgkmcnt(1)
	v_add_f32_e32 v4, v4, v18
	v_add_u32_e32 v16, s25, v2
	s_waitcnt lgkmcnt(0)
	v_add_f32_e32 v4, v4, v20
	v_lshlrev_b64 v[0:1], 11, v[16:17]
	v_add_u32_e32 v16, s24, v2
	v_lshlrev_b64 v[2:3], 11, v[16:17]
	v_lshl_add_u64 v[2:3], s[4:5], 0, v[2:3]
	v_lshl_add_u64 v[0:1], v[24:25], 0, v[0:1]
	v_lshl_add_u64 v[2:3], v[2:3], 0, v[22:23]
	global_load_ushort v16, v[0:1], off
	s_waitcnt vmcnt(2)
	v_lshlrev_b32_e32 v6, 16, v32
	s_waitcnt vmcnt(1)
	v_lshlrev_b32_e32 v8, 16, v33
	v_fmac_f32_e32 v6, v4, v8
	v_bfe_u32 v4, v6, 16, 1
	v_add3_u32 v4, v6, v4, s19
	global_store_short_d16_hi v[26:27], v4, off
	global_load_ushort v2, v[2:3], off
	v_add_f32_e32 v3, 0, v5
	v_add_f32_e32 v3, v3, v7
	v_add_f32_e32 v3, v3, v9
	v_add_f32_e32 v3, v3, v11
	v_add_f32_e32 v3, v3, v13
	v_add_f32_e32 v3, v3, v15
	v_add_f32_e32 v3, v3, v19
	v_add_f32_e32 v3, v3, v21
	s_waitcnt vmcnt(2)
	v_lshlrev_b32_e32 v4, 16, v16
	s_waitcnt vmcnt(0)
	v_lshlrev_b32_e32 v2, 16, v2
	v_fmac_f32_e32 v4, v3, v2
	v_bfe_u32 v2, v4, 16, 1
	v_add3_u32 v2, v4, v2, s19
	global_store_short_d16_hi v[0:1], v2, off
	s_barrier
	s_cbranch_scc0 .LBB0_1035

; #define MFMA32(a, b, c) __builtin_amdgcn_mfma_f32_32x32x16_bf16((a), (b), (c), 0, 0, 0)
; template <int NB, class F> __device__ __forceinline__ void small_gemm(const bf16* A, int K, const bf16* const (&Bs)[NB], int rg, int wave_s, LAS unsigned char* lds, const F& epi) {
;     ...
;     const bf16* ap = A + (size_t)(ROW_S0 + 32 * rg + r32) * K + w * kw + 8 * hi;
;     const bf16* bp[NB];
; #pragma unroll
;     for (int nb = 0; nb < NB; ++nb) bp[nb] = Bs[nb] + (size_t)r32 * K + w * kw + 8 * hi;
;     f32x16 acc[NB];
; #pragma unroll
;     for (int nb = 0; nb < NB; ++nb)
; #pragma unroll
;         for (int i = 0; i < 16; ++i) acc[nb][i] = 0.f;
;     for (int s0 = 0; s0 < steps; s0 += 8) {
;         bf16x8 af[8], bfr[NB][8];
; #pragma unroll
;         for (int s = 0; s < 8; ++s) if (s0 + s < steps) { af[s] = *(const bf16x8*)(ap + 16 * (s0 + s));
; #pragma unroll
;             for (int nb = 0; nb < NB; ++nb) bfr[nb][s] = *(const bf16x8*)(bp[nb] + 16 * (s0 + s)); }
; #pragma unroll
;         for (int s = 0; s < 8; ++s) if (s0 + s < steps) {
; #pragma unroll
;             for (int nb = 0; nb < NB; ++nb) acc[nb] = MFMA32(af[s], bfr[nb][s], acc[nb]); }
.LBB0_1115:
	s_ashr_i32 s12, s26, 3
	s_lshl_b32 s16, s12, 6
	s_ashr_i32 s17, s16, 31
	s_lshl_b64 s[40:41], s[16:17], 11
	s_add_u32 s40, s18, s40
	s_addc_u32 s41, s19, s41
	s_or_b32 s42, s16, 32
	s_mov_b32 s13, -1
	s_ashr_i32 s43, s42, 31
	s_lshl_b64 s[42:43], s[42:43], 11
	v_mbcnt_lo_u32_b32 v0, s13, 0
	v_mbcnt_hi_u32_b32 v0, s13, v0
	s_add_u32 s42, s18, s42
	v_add_u32_e32 v45, s33, v0
	s_addc_u32 s43, s19, s43
	s_and_b32 s13, s23, 0xe0
	s_waitcnt vmcnt(0)
	v_and_b32_e32 v72, 31, v45
	v_or_b32_e32 v0, s13, v72
	v_bfe_u32 v73, v45, 5, 1
	v_lshl_or_b32 v32, v0, 11, v38
	v_lshlrev_b32_e32 v10, 4, v73
	v_mov_b32_e32 v11, v33
	v_lshl_add_u64 v[0:1], s[4:5], 0, v[32:33]
	v_lshl_add_u64 v[66:67], v[0:1], 0, v[10:11]
	v_lshlrev_b32_e32 v8, 11, v72
	v_mov_b32_e32 v9, v33
	v_lshl_add_u64 v[4:5], s[40:41], 0, v[8:9]
	v_lshl_add_u64 v[4:5], v[4:5], 0, s[2:3]
	v_lshl_add_u64 v[68:69], v[4:5], 0, v[10:11]
	v_lshl_add_u64 v[8:9], s[42:43], 0, v[8:9]
	v_lshl_add_u64 v[8:9], v[8:9], 0, s[2:3]
	v_lshl_add_u64 v[70:71], v[8:9], 0, v[10:11]
	global_load_dwordx4 v[76:79], v[66:67], off
	global_load_dwordx4 v[80:83], v[68:69], off
	global_load_dwordx4 v[84:87], v[70:71], off
	global_load_dwordx4 v[88:91], v[66:67], off offset:32
	global_load_dwordx4 v[92:95], v[68:69], off offset:32
	global_load_dwordx4 v[96:99], v[70:71], off offset:32
	global_load_dwordx4 v[100:103], v[66:67], off offset:64
	global_load_dwordx4 v[104:107], v[68:69], off offset:64
	global_load_dwordx4 v[108:111], v[70:71], off offset:64
	global_load_dwordx4 v[112:115], v[66:67], off offset:96
	global_load_dwordx4 v[116:119], v[68:69], off offset:96
	global_load_dwordx4 v[120:123], v[70:71], off offset:96
	global_load_dwordx4 v[124:127], v[66:67], off offset:128
	global_load_dwordx4 v[128:131], v[68:69], off offset:128
	global_load_dwordx4 v[132:135], v[70:71], off offset:128
	global_load_dwordx4 v[136:139], v[66:67], off offset:160
	global_load_dwordx4 v[140:143], v[68:69], off offset:160
	global_load_dwordx4 v[144:147], v[70:71], off offset:160
	global_load_dwordx4 v[148:151], v[66:67], off offset:192
	global_load_dwordx4 v[152:155], v[68:69], off offset:192
	global_load_dwordx4 v[156:159], v[70:71], off offset:192
	global_load_dwordx4 v[160:163], v[66:67], off offset:224
	global_load_dwordx4 v[164:167], v[68:69], off offset:224
	global_load_dwordx4 v[168:171], v[70:71], off offset:224
	s_add_i32 s13, s13, s22
	v_and_b32_e32 v32, 63, v45
	v_lshl_add_u32 v32, v32, 2, 0
	v_add_u32_e32 v45, s20, v32
	v_cmp_lt_i32_e32 vcc, v39, v40
	s_waitcnt vmcnt(22)
	v_mfma_f32_32x32x16_bf16 v[16:31], v[76:79], v[80:83], 0
	s_waitcnt vmcnt(21)
	v_mfma_f32_32x32x16_bf16 v[0:15], v[76:79], v[84:87], 0
	s_waitcnt vmcnt(19)
	v_mfma_f32_32x32x16_bf16 v[16:31], v[88:91], v[92:95], v[16:31]
	s_waitcnt vmcnt(18)
	v_mfma_f32_32x32x16_bf16 v[0:15], v[88:91], v[96:99], v[0:15]
	s_waitcnt vmcnt(16)
	v_mfma_f32_32x32x16_bf16 v[16:31], v[100:103], v[104:107], v[16:31]
	s_waitcnt vmcnt(15)
	v_mfma_f32_32x32x16_bf16 v[0:15], v[100:103], v[108:111], v[0:15]
	s_waitcnt vmcnt(13)
	v_mfma_f32_32x32x16_bf16 v[16:31], v[112:115], v[116:119], v[16:31]
	s_waitcnt vmcnt(12)
	v_mfma_f32_32x32x16_bf16 v[0:15], v[112:115], v[120:123], v[0:15]
	s_waitcnt vmcnt(10)
	v_mfma_f32_32x32x16_bf16 v[16:31], v[124:127], v[128:131], v[16:31]
	s_waitcnt vmcnt(9)
	v_mfma_f32_32x32x16_bf16 v[0:15], v[124:127], v[132:135], v[0:15]
	s_waitcnt vmcnt(7)
	v_mfma_f32_32x32x16_bf16 v[16:31], v[136:139], v[140:143], v[16:31]
	s_waitcnt vmcnt(6)
	v_mfma_f32_32x32x16_bf16 v[0:15], v[136:139], v[144:147], v[0:15]
	s_waitcnt vmcnt(4)
	v_mfma_f32_32x32x16_bf16 v[16:31], v[148:151], v[152:155], v[16:31]
	s_waitcnt vmcnt(3)
	v_mfma_f32_32x32x16_bf16 v[0:15], v[148:151], v[156:159], v[0:15]
	s_waitcnt vmcnt(1)
	v_mfma_f32_32x32x16_bf16 v[16:31], v[160:163], v[164:167], v[16:31]
	s_waitcnt vmcnt(0)
	v_mfma_f32_32x32x16_bf16 v[0:15], v[160:163], v[168:171], v[0:15]
	v_mov_b32_e32 v37, v33
	v_lshl_or_b32 v36, v73, 2, s13
	v_or_b32_e32 v34, s16, v72
	v_ashrrev_i32_e32 v35, 31, v34
	v_lshlrev_b64 v[46:47], 12, v[36:37]
	v_lshl_add_u64 v[46:47], s[38:39], 0, v[46:47]
	v_lshl_add_u64 v[46:47], v[34:35], 2, v[46:47]
	s_nop 6
	ds_write2st64_b32 v45, v16, v17 offset1:1
	ds_write2st64_b32 v45, v18, v19 offset0:2 offset1:3
	ds_write2st64_b32 v45, v20, v21 offset0:4 offset1:5
	ds_write2st64_b32 v45, v22, v23 offset0:6 offset1:7
	ds_write2st64_b32 v45, v24, v25 offset0:8 offset1:9
	ds_write2st64_b32 v45, v26, v27 offset0:10 offset1:11
	ds_write2st64_b32 v45, v28, v29 offset0:12 offset1:13
	ds_write2st64_b32 v45, v30, v31 offset0:14 offset1:15
	ds_write2st64_b32 v45, v0, v1 offset0:16 offset1:17
	ds_write2st64_b32 v45, v2, v3 offset0:18 offset1:19
	ds_write2st64_b32 v45, v4, v5 offset0:20 offset1:21
	ds_write2st64_b32 v45, v6, v7 offset0:22 offset1:23
	ds_write2st64_b32 v45, v8, v9 offset0:24 offset1:25
	ds_write2st64_b32 v45, v10, v11 offset0:26 offset1:27
	ds_write2st64_b32 v45, v12, v13 offset0:28 offset1:29
	ds_write2st64_b32 v45, v14, v15 offset0:30 offset1:31
	s_waitcnt lgkmcnt(0)
	s_barrier
; #define LAS __attribute__((address_space(3)))
; __device__ __forceinline__ unsigned f2bf(float f) { unsigned u = __builtin_bit_cast(unsigned, f); return (u + 0x7fffu + ((u >> 16) & 1u)) >> 16; }
; __device__ __forceinline__ int crow(int r, int hi) { return (r & 3) + 8 * (r >> 2) + 4 * hi; }
; template <int NB, class F> __device__ __forceinline__ void small_gemm(const bf16* A, int K, const bf16* const (&Bs)[NB], int rg, int wave_s, LAS unsigned char* lds, const F& epi) {
;     ...
;     LAS float* P = (LAS float*)lds;
; #pragma unroll
;     for (int nb = 0; nb < NB; ++nb)
; #pragma unroll
;         for (int i = 0; i < 16; ++i) P[((w * NB + nb) * 16 + i) * 64 + lane] = acc[nb][i];
;     __syncthreads();
;     float v[NB][2];
; #pragma unroll
;     for (int nb = 0; nb < NB; ++nb)
; #pragma unroll
;         for (int ii = 0; ii < 2; ++ii) { float t = 0.f;
; #pragma unroll
;             for (int ww = 0; ww < 8; ++ww) t += P[((ww * NB + nb) * 16 + 2 * w + ii) * 64 + lane];
;             v[nb][ii] = t; }
;     epi(v, w, r32, hi);
; __global__ void __launch_bounds__(512, 2) hybrid_fwd(Ctx c) {
;     ...
;             for (int ii = 0; ii < 2; ++ii) { const int sr = 32 * rg + crow(2 * w + ii, hi), row = ROW_S0 + sr; float ss = 0.f;
; #pragma unroll
;                 for (int nb = 0; nb < 2; ++nb) { const int col = 64 * cg + 32 * nb + r32; const float x = c.x_sample[(size_t)sr * D + col] + v[nb][ii];
;                     HB[(size_t)row * D + col] = (bf16)f2bf(x); ss += x * x; }
;                 ss += __shfl_xor(ss, 1); ss += __shfl_xor(ss, 2); ss += __shfl_xor(ss, 4); ss += __shfl_xor(ss, 8); ss += __shfl_xor(ss, 16);
;                 if (r32 == 0) SS[(size_t)row * 16 + cg] = ss; } });
	global_load_dword v45, v[46:47], off
	global_load_dword v48, v[46:47], off offset:128
	v_cndmask_b32_e32 v0, v212, v39, vcc
	v_add_u32_e32 v30, s21, v32
	v_lshlrev_b32_e32 v37, 2, v0
	ds_read2st64_b32 v[16:17], v30 offset1:1
	ds_read2st64_b32 v[0:1], v30 offset0:32 offset1:33
	ds_read2st64_b32 v[2:3], v30 offset0:48 offset1:49
	ds_read2st64_b32 v[24:25], v30 offset0:16 offset1:17
	ds_read2st64_b32 v[18:19], v30 offset0:64 offset1:65
	ds_read2st64_b32 v[4:5], v30 offset0:96 offset1:97
	ds_read2st64_b32 v[6:7], v30 offset0:112 offset1:113
	ds_read2st64_b32 v[26:27], v30 offset0:80 offset1:81
	ds_read2st64_b32 v[20:21], v30 offset0:128 offset1:129
	ds_read2st64_b32 v[8:9], v30 offset0:160 offset1:161
	ds_read2st64_b32 v[10:11], v30 offset0:176 offset1:177
	ds_read2st64_b32 v[28:29], v30 offset0:144 offset1:145
	ds_read2st64_b32 v[22:23], v30 offset0:192 offset1:193
	ds_read2st64_b32 v[12:13], v30 offset0:224 offset1:225
	ds_read2st64_b32 v[14:15], v30 offset0:240 offset1:241
	ds_read2st64_b32 v[30:31], v30 offset0:208 offset1:209
	s_waitcnt lgkmcnt(12)
	v_add_f32_e32 v24, 0, v24
	v_add_f32_e32 v16, 0, v16
	v_add_f32_e32 v2, v24, v2
	v_add_f32_e32 v0, v16, v0
	s_waitcnt lgkmcnt(8)
	v_add_f32_e32 v2, v2, v26
	v_add_f32_e32 v0, v0, v18
	v_add_f32_e32 v2, v2, v6
	v_add_f32_e32 v0, v0, v4
	s_waitcnt lgkmcnt(4)
	v_add_f32_e32 v2, v2, v28
	v_add_f32_e32 v0, v0, v20
	v_add_f32_e32 v2, v2, v10
	v_add_f32_e32 v0, v0, v8
	s_waitcnt lgkmcnt(0)
	v_add_f32_e32 v2, v2, v30
	v_add_f32_e32 v0, v0, v22
	v_add_f32_e32 v2, v2, v14
	v_add_f32_e32 v0, v0, v12
	v_cmp_lt_i32_e32 vcc, v41, v40
	v_add_u32_e32 v32, 0x8000, v36
	s_waitcnt vmcnt(1)
	v_add_f32_e32 v8, v0, v45
	s_waitcnt vmcnt(0)
	v_add_f32_e32 v12, v2, v48
	v_mul_f32_e32 v0, v12, v12
	v_fmac_f32_e32 v0, v8, v8
	ds_bpermute_b32 v4, v37, v0
	v_cndmask_b32_e32 v46, v212, v41, vcc
	v_lshlrev_b32_e32 v6, 2, v46
	v_cmp_lt_i32_e32 vcc, v42, v40
	v_lshlrev_b64 v[46:47], 11, v[32:33]
	s_waitcnt lgkmcnt(0)
	v_add_f32_e32 v0, v0, v4
	ds_bpermute_b32 v10, v6, v0
	v_cndmask_b32_e32 v2, v212, v42, vcc
	v_lshlrev_b32_e32 v2, 2, v2
	v_cmp_lt_i32_e32 vcc, v43, v40
	v_lshl_add_u64 v[46:47], s[28:29], 0, v[46:47]
	s_waitcnt lgkmcnt(0)
	v_add_f32_e32 v10, v0, v10
	ds_bpermute_b32 v16, v2, v10
	v_cndmask_b32_e32 v4, v212, v43, vcc
	v_cmp_lt_i32_e32 vcc, v44, v40
	v_lshlrev_b32_e32 v4, 2, v4
	v_lshl_add_u64 v[46:47], v[34:35], 1, v[46:47]
	v_cndmask_b32_e32 v14, v212, v44, vcc
	s_waitcnt lgkmcnt(0)
	v_add_f32_e32 v10, v10, v16
	v_lshlrev_b32_e32 v0, 2, v14
	ds_bpermute_b32 v14, v4, v10
	v_bfe_u32 v16, v8, 16, 1
	v_add3_u32 v16, v8, v16, s25
	v_cmp_eq_u32_e32 vcc, 0, v72
	global_store_short_d16_hi v[46:47], v16, off
	s_waitcnt lgkmcnt(0)
	v_add_f32_e32 v8, v10, v14
	ds_bpermute_b32 v10, v0, v8
	v_bfe_u32 v14, v12, 16, 1
	v_add3_u32 v12, v12, v14, s25
	global_store_short_d16_hi v[46:47], v12, off offset:64
	s_and_saveexec_b64 s[16:17], vcc
	s_cbranch_execz .LBB0_1117
	v_lshlrev_b64 v[46:47], 6, v[32:33]
	v_lshl_add_u64 v[46:47], s[10:11], 0, v[46:47]
	s_ashr_i32 s13, s12, 31
	s_waitcnt lgkmcnt(0)
	v_add_f32_e32 v8, v8, v10
	v_lshl_add_u64 v[46:47], s[12:13], 2, v[46:47]
	global_store_dword v[46:47], v8, off

; #define MFMA32(a, b, c) __builtin_amdgcn_mfma_f32_32x32x16_bf16((a), (b), (c), 0, 0, 0)
; template <int NB, class F> __device__ __forceinline__ void small_gemm(const bf16* A, int K, const bf16* const (&Bs)[NB], int rg, int wave_s, LAS unsigned char* lds, const F& epi) {
;     ...
;     const bf16* ap = A + (size_t)(ROW_S0 + 32 * rg + r32) * K + w * kw + 8 * hi;
;     const bf16* bp[NB];
; #pragma unroll
;     for (int nb = 0; nb < NB; ++nb) bp[nb] = Bs[nb] + (size_t)r32 * K + w * kw + 8 * hi;
;     f32x16 acc[NB];
; #pragma unroll
;     for (int nb = 0; nb < NB; ++nb)
; #pragma unroll
;         for (int i = 0; i < 16; ++i) acc[nb][i] = 0.f;
;     for (int s0 = 0; s0 < steps; s0 += 8) {
;         bf16x8 af[8], bfr[NB][8];
; #pragma unroll
;         for (int s = 0; s < 8; ++s) if (s0 + s < steps) { af[s] = *(const bf16x8*)(ap + 16 * (s0 + s));
; #pragma unroll
;             for (int nb = 0; nb < NB; ++nb) bfr[nb][s] = *(const bf16x8*)(bp[nb] + 16 * (s0 + s)); }
; #pragma unroll
;         for (int s = 0; s < 8; ++s) if (s0 + s < steps) {
; #pragma unroll
;             for (int nb = 0; nb < NB; ++nb) acc[nb] = MFMA32(af[s], bfr[nb][s], acc[nb]); }
.LBB0_1319:
	s_ashr_i32 s10, s24, 3
	s_lshl_b32 s11, s10, 6
	s_ashr_i32 s12, s11, 31
	s_mul_i32 s13, s10, 0x58000
	s_mul_hi_i32 s25, s11, 0x1600
	s_add_u32 s26, s16, s13
	s_addc_u32 s27, s17, s25
	s_or_b32 s13, s11, 32
	s_mul_hi_i32 s25, s13, 0x1600
	s_mulk_i32 s13, 0x1600
	s_add_u32 s36, s16, s13
	s_mov_b32 s13, -1
	s_addc_u32 s37, s17, s25
	v_mbcnt_lo_u32_b32 v0, s13, 0
	v_mbcnt_hi_u32_b32 v0, s13, v0
	s_waitcnt vmcnt(0)
	v_add_u32_e32 v70, s33, v0
	s_and_b32 s13, s21, 0xe0
	v_and_b32_e32 v71, 31, v70
	v_or_b32_e32 v0, s13, v71
	v_or_b32_e32 v0, 0x8000, v0
	v_bfe_u32 v72, v70, 5, 1
	v_mul_u32_u24_e32 v32, 0x1600, v0
	v_mul_u32_u24_e32 v0, 0xb00, v71
	v_lshlrev_b32_e32 v8, 1, v0
	v_lshlrev_b32_e32 v10, 4, v72
	v_mov_b32_e32 v11, v33
	v_lshl_add_u64 v[0:1], s[4:5], 0, v[32:33]
	v_lshl_add_u64 v[34:35], v[0:1], 0, v[10:11]
	v_mov_b32_e32 v9, v33
	v_lshl_add_u64 v[4:5], s[26:27], 0, v[8:9]
	v_lshl_add_u64 v[4:5], v[4:5], 0, s[2:3]
	v_lshl_add_u64 v[66:67], v[4:5], 0, v[10:11]
	v_lshl_add_u64 v[8:9], s[36:37], 0, v[8:9]
	v_lshl_add_u64 v[8:9], v[8:9], 0, s[2:3]
	v_lshl_add_u64 v[68:69], v[8:9], 0, v[10:11]
	global_load_dwordx4 v[76:79], v[34:35], off
	global_load_dwordx4 v[80:83], v[66:67], off
	global_load_dwordx4 v[84:87], v[68:69], off
	global_load_dwordx4 v[88:91], v[34:35], off offset:32
	global_load_dwordx4 v[92:95], v[66:67], off offset:32
	global_load_dwordx4 v[96:99], v[68:69], off offset:32
	global_load_dwordx4 v[100:103], v[34:35], off offset:64
	global_load_dwordx4 v[104:107], v[66:67], off offset:64
	global_load_dwordx4 v[108:111], v[68:69], off offset:64
	global_load_dwordx4 v[112:115], v[34:35], off offset:96
	global_load_dwordx4 v[116:119], v[66:67], off offset:96
	global_load_dwordx4 v[120:123], v[68:69], off offset:96
	global_load_dwordx4 v[124:127], v[34:35], off offset:128
	global_load_dwordx4 v[128:131], v[66:67], off offset:128
	global_load_dwordx4 v[132:135], v[68:69], off offset:128
	global_load_dwordx4 v[136:139], v[34:35], off offset:160
	global_load_dwordx4 v[140:143], v[66:67], off offset:160
	global_load_dwordx4 v[144:147], v[68:69], off offset:160
	global_load_dwordx4 v[148:151], v[34:35], off offset:192
	global_load_dwordx4 v[152:155], v[66:67], off offset:192
	global_load_dwordx4 v[156:159], v[68:69], off offset:192
	global_load_dwordx4 v[160:163], v[34:35], off offset:224
	global_load_dwordx4 v[164:167], v[66:67], off offset:224
	global_load_dwordx4 v[168:171], v[68:69], off offset:224
	global_load_dwordx4 v[172:175], v[34:35], off offset:256
	global_load_dwordx4 v[176:179], v[66:67], off offset:256
	global_load_dwordx4 v[184:187], v[68:69], off offset:256
	global_load_dwordx4 v[188:191], v[34:35], off offset:288
	global_load_dwordx4 v[192:195], v[66:67], off offset:288
	global_load_dwordx4 v[196:199], v[68:69], off offset:288
	global_load_dwordx4 v[200:203], v[34:35], off offset:320
	global_load_dwordx4 v[204:207], v[66:67], off offset:320
	global_load_dwordx4 v[208:211], v[68:69], off offset:320
	global_load_dwordx4 v[216:219], v[34:35], off offset:352
	global_load_dwordx4 v[220:223], v[66:67], off offset:352
	global_load_dwordx4 v[224:227], v[68:69], off offset:352
	global_load_dwordx4 v[228:231], v[34:35], off offset:384
	global_load_dwordx4 v[232:235], v[66:67], off offset:384
	global_load_dwordx4 v[236:239], v[68:69], off offset:384
	global_load_dwordx4 v[240:243], v[34:35], off offset:416
	global_load_dwordx4 v[244:247], v[66:67], off offset:416
	global_load_dwordx4 v[248:251], v[68:69], off offset:416
	v_and_b32_e32 v32, 63, v70
	s_add_i32 s13, s20, s13
	v_cmp_lt_i32_e32 vcc, v36, v37
	s_waitcnt vmcnt(40)
	v_mfma_f32_32x32x16_bf16 v[16:31], v[76:79], v[80:83], 0
	s_waitcnt vmcnt(39)
	v_mfma_f32_32x32x16_bf16 v[0:15], v[76:79], v[84:87], 0
	global_load_dwordx4 v[76:79], v[34:35], off offset:448
	global_load_dwordx4 v[80:83], v[66:67], off offset:448
	global_load_dwordx4 v[84:87], v[68:69], off offset:448
	s_waitcnt vmcnt(40)
	v_mfma_f32_32x32x16_bf16 v[16:31], v[88:91], v[92:95], v[16:31]
	s_waitcnt vmcnt(39)
	v_mfma_f32_32x32x16_bf16 v[0:15], v[88:91], v[96:99], v[0:15]
	global_load_dwordx4 v[88:91], v[34:35], off offset:480
	global_load_dwordx4 v[92:95], v[66:67], off offset:480
	global_load_dwordx4 v[96:99], v[68:69], off offset:480
	s_waitcnt vmcnt(40)
	v_mfma_f32_32x32x16_bf16 v[16:31], v[100:103], v[104:107], v[16:31]
	s_waitcnt vmcnt(39)
	v_mfma_f32_32x32x16_bf16 v[0:15], v[100:103], v[108:111], v[0:15]
	global_load_dwordx4 v[100:103], v[34:35], off offset:512
	global_load_dwordx4 v[104:107], v[66:67], off offset:512
	global_load_dwordx4 v[108:111], v[68:69], off offset:512
	s_waitcnt vmcnt(40)
	v_mfma_f32_32x32x16_bf16 v[16:31], v[112:115], v[116:119], v[16:31]
	s_waitcnt vmcnt(39)
	v_mfma_f32_32x32x16_bf16 v[0:15], v[112:115], v[120:123], v[0:15]
	global_load_dwordx4 v[112:115], v[34:35], off offset:544
	global_load_dwordx4 v[116:119], v[66:67], off offset:544
	global_load_dwordx4 v[120:123], v[68:69], off offset:544
	s_waitcnt vmcnt(40)
	v_mfma_f32_32x32x16_bf16 v[16:31], v[124:127], v[128:131], v[16:31]
	s_waitcnt vmcnt(39)
	v_mfma_f32_32x32x16_bf16 v[0:15], v[124:127], v[132:135], v[0:15]
	global_load_dwordx4 v[124:127], v[34:35], off offset:576
	global_load_dwordx4 v[128:131], v[66:67], off offset:576
	global_load_dwordx4 v[132:135], v[68:69], off offset:576
	s_waitcnt vmcnt(40)
	v_mfma_f32_32x32x16_bf16 v[16:31], v[136:139], v[140:143], v[16:31]
	s_waitcnt vmcnt(39)
	v_mfma_f32_32x32x16_bf16 v[0:15], v[136:139], v[144:147], v[0:15]
	global_load_dwordx4 v[136:139], v[34:35], off offset:608
	global_load_dwordx4 v[140:143], v[66:67], off offset:608
	global_load_dwordx4 v[144:147], v[68:69], off offset:608
	s_waitcnt vmcnt(40)
; #define LAS __attribute__((address_space(3)))
; #define MFMA32(a, b, c) __builtin_amdgcn_mfma_f32_32x32x16_bf16((a), (b), (c), 0, 0, 0)
; template <int NB, class F> __device__ __forceinline__ void small_gemm(const bf16* A, int K, const bf16* const (&Bs)[NB], int rg, int wave_s, LAS unsigned char* lds, const F& epi) {
;     ...
;     for (int s0 = 0; s0 < steps; s0 += 8) {
;         bf16x8 af[8], bfr[NB][8];
; #pragma unroll
;         for (int s = 0; s < 8; ++s) if (s0 + s < steps) { af[s] = *(const bf16x8*)(ap + 16 * (s0 + s));
; #pragma unroll
;             for (int nb = 0; nb < NB; ++nb) bfr[nb][s] = *(const bf16x8*)(bp[nb] + 16 * (s0 + s)); }
; #pragma unroll
;         for (int s = 0; s < 8; ++s) if (s0 + s < steps) {
; #pragma unroll
;             for (int nb = 0; nb < NB; ++nb) acc[nb] = MFMA32(af[s], bfr[nb][s], acc[nb]); }
;     }
;     LAS float* P = (LAS float*)lds;
; #pragma unroll
;     for (int nb = 0; nb < NB; ++nb)
; #pragma unroll
;         for (int i = 0; i < 16; ++i) P[((w * NB + nb) * 16 + i) * 64 + lane] = acc[nb][i];
	v_mfma_f32_32x32x16_bf16 v[16:31], v[148:151], v[152:155], v[16:31]
	s_waitcnt vmcnt(39)
	v_mfma_f32_32x32x16_bf16 v[0:15], v[148:151], v[156:159], v[0:15]
	global_load_dwordx4 v[148:151], v[34:35], off offset:640
	global_load_dwordx4 v[152:155], v[66:67], off offset:640
	global_load_dwordx4 v[156:159], v[68:69], off offset:640
	s_waitcnt vmcnt(40)
	v_mfma_f32_32x32x16_bf16 v[16:31], v[160:163], v[164:167], v[16:31]
	s_waitcnt vmcnt(39)
	v_mfma_f32_32x32x16_bf16 v[0:15], v[160:163], v[168:171], v[0:15]
	global_load_dwordx4 v[160:163], v[34:35], off offset:672
	global_load_dwordx4 v[164:167], v[66:67], off offset:672
	global_load_dwordx4 v[168:171], v[68:69], off offset:672
	s_waitcnt vmcnt(40)
	v_mfma_f32_32x32x16_bf16 v[16:31], v[172:175], v[176:179], v[16:31]
	s_waitcnt vmcnt(39)
	v_mfma_f32_32x32x16_bf16 v[0:15], v[172:175], v[184:187], v[0:15]
	s_waitcnt vmcnt(37)
	v_mfma_f32_32x32x16_bf16 v[16:31], v[188:191], v[192:195], v[16:31]
	s_waitcnt vmcnt(36)
	v_mfma_f32_32x32x16_bf16 v[0:15], v[188:191], v[196:199], v[0:15]
	s_waitcnt vmcnt(34)
	v_mfma_f32_32x32x16_bf16 v[16:31], v[200:203], v[204:207], v[16:31]
	s_waitcnt vmcnt(33)
	v_mfma_f32_32x32x16_bf16 v[0:15], v[200:203], v[208:211], v[0:15]
	s_waitcnt vmcnt(31)
	v_mfma_f32_32x32x16_bf16 v[16:31], v[216:219], v[220:223], v[16:31]
	s_waitcnt vmcnt(30)
	v_mfma_f32_32x32x16_bf16 v[0:15], v[216:219], v[224:227], v[0:15]
	s_waitcnt vmcnt(28)
	v_mfma_f32_32x32x16_bf16 v[16:31], v[228:231], v[232:235], v[16:31]
	s_waitcnt vmcnt(27)
	v_mfma_f32_32x32x16_bf16 v[0:15], v[228:231], v[236:239], v[0:15]
	s_waitcnt vmcnt(25)
	v_mfma_f32_32x32x16_bf16 v[16:31], v[240:243], v[244:247], v[16:31]
	s_waitcnt vmcnt(24)
	v_mfma_f32_32x32x16_bf16 v[0:15], v[240:243], v[248:251], v[0:15]
	s_waitcnt vmcnt(22)
	v_mfma_f32_32x32x16_bf16 v[16:31], v[76:79], v[80:83], v[16:31]
	s_waitcnt vmcnt(21)
	v_mfma_f32_32x32x16_bf16 v[0:15], v[76:79], v[84:87], v[0:15]
	s_waitcnt vmcnt(19)
	v_mfma_f32_32x32x16_bf16 v[16:31], v[88:91], v[92:95], v[16:31]
	s_waitcnt vmcnt(18)
	v_mfma_f32_32x32x16_bf16 v[0:15], v[88:91], v[96:99], v[0:15]
	s_waitcnt vmcnt(16)
	v_mfma_f32_32x32x16_bf16 v[16:31], v[100:103], v[104:107], v[16:31]
	s_waitcnt vmcnt(15)
	v_mfma_f32_32x32x16_bf16 v[0:15], v[100:103], v[108:111], v[0:15]
	s_waitcnt vmcnt(13)
	v_mfma_f32_32x32x16_bf16 v[16:31], v[112:115], v[116:119], v[16:31]
	s_waitcnt vmcnt(12)
	v_mfma_f32_32x32x16_bf16 v[0:15], v[112:115], v[120:123], v[0:15]
	s_waitcnt vmcnt(10)
	v_mfma_f32_32x32x16_bf16 v[16:31], v[124:127], v[128:131], v[16:31]
	s_waitcnt vmcnt(9)
	v_mfma_f32_32x32x16_bf16 v[0:15], v[124:127], v[132:135], v[0:15]
	s_waitcnt vmcnt(7)
	v_mfma_f32_32x32x16_bf16 v[16:31], v[136:139], v[140:143], v[16:31]
	s_waitcnt vmcnt(6)
	v_mfma_f32_32x32x16_bf16 v[0:15], v[136:139], v[144:147], v[0:15]
	s_waitcnt vmcnt(4)
	v_mfma_f32_32x32x16_bf16 v[16:31], v[148:151], v[152:155], v[16:31]
	s_waitcnt vmcnt(3)
	v_mfma_f32_32x32x16_bf16 v[0:15], v[148:151], v[156:159], v[0:15]
	s_waitcnt vmcnt(1)
	v_mfma_f32_32x32x16_bf16 v[16:31], v[160:163], v[164:167], v[16:31]
	s_waitcnt vmcnt(0)
	v_mfma_f32_32x32x16_bf16 v[0:15], v[160:163], v[168:171], v[0:15]
	v_lshl_add_u32 v34, v32, 2, 0
	v_add_u32_e32 v32, s18, v34
	v_add_u32_e32 v34, s19, v34
	s_nop 8
	ds_write2st64_b32 v32, v16, v17 offset1:1
	ds_write2st64_b32 v32, v18, v19 offset0:2 offset1:3
	ds_write2st64_b32 v32, v20, v21 offset0:4 offset1:5
	ds_write2st64_b32 v32, v22, v23 offset0:6 offset1:7
	ds_write2st64_b32 v32, v24, v25 offset0:8 offset1:9
	ds_write2st64_b32 v32, v26, v27 offset0:10 offset1:11
	ds_write2st64_b32 v32, v28, v29 offset0:12 offset1:13
	ds_write2st64_b32 v32, v30, v31 offset0:14 offset1:15
	s_nop 11
	ds_write2st64_b32 v32, v0, v1 offset0:16 offset1:17
	ds_write2st64_b32 v32, v2, v3 offset0:18 offset1:19
	ds_write2st64_b32 v32, v4, v5 offset0:20 offset1:21
	ds_write2st64_b32 v32, v6, v7 offset0:22 offset1:23
	ds_write2st64_b32 v32, v8, v9 offset0:24 offset1:25
	ds_write2st64_b32 v32, v10, v11 offset0:26 offset1:27
	ds_write2st64_b32 v32, v12, v13 offset0:28 offset1:29
	ds_write2st64_b32 v32, v14, v15 offset0:30 offset1:31
	v_lshl_or_b32 v32, v72, 2, s13
	v_or_b32_e32 v0, s11, v71
	v_mov_b32_e32 v1, s12
	v_lshlrev_b64 v[2:3], 10, v[32:33]
	v_lshl_add_u64 v[2:3], v[2:3], 0, v[0:1]
	v_lshlrev_b64 v[42:43], 1, v[2:3]
	v_lshl_add_u64 v[2:3], s[28:29], 0, v[42:43]
	v_lshl_add_u64 v[44:45], s[6:7], 0, v[42:43]
	v_or_b32_e32 v42, 64, v42
	s_waitcnt lgkmcnt(0)
	s_barrier
; __device__ __forceinline__ unsigned f2bf(float f) { unsigned u = __builtin_bit_cast(unsigned, f); return (u + 0x7fffu + ((u >> 16) & 1u)) >> 16; }
; __device__ __forceinline__ int crow(int r, int hi) { return (r & 3) + 8 * (r >> 2) + 4 * hi; }
; template <int NB, class F> __device__ __forceinline__ void small_gemm(const bf16* A, int K, const bf16* const (&Bs)[NB], int rg, int wave_s, LAS unsigned char* lds, const F& epi) {
;     ...
;     float v[NB][2];
; #pragma unroll
;     for (int nb = 0; nb < NB; ++nb)
; #pragma unroll
;         for (int ii = 0; ii < 2; ++ii) { float t = 0.f;
; #pragma unroll
;             for (int ww = 0; ww < 8; ++ww) t += P[((ww * NB + nb) * 16 + 2 * w + ii) * 64 + lane];
;             v[nb][ii] = t; }
;     epi(v, w, r32, hi);
; __global__ void __launch_bounds__(512, 2) hybrid_fwd(Ctx c) {
;     ...
;             for (int ii = 0; ii < 2; ++ii) { const int sr = 32 * rg + crow(2 * w + ii, hi), row = ROW_S0 + sr; float ss = 0.f;
; #pragma unroll
;                 for (int nb = 0; nb < 2; ++nb) { const size_t idx = (size_t)row * D + 64 * cg + 32 * nb + r32; const float x = bf2f(((const bf16*)(ws + WS_H1B))[idx]) + v[nb][ii]; ((bf16*)(ws + WS_H2B))[idx] = (bf16)f2bf(x); ss += x * x; }
;                 ss += __shfl_xor(ss, 1); ss += __shfl_xor(ss, 2); ss += __shfl_xor(ss, 4); ss += __shfl_xor(ss, 8); ss += __shfl_xor(ss, 16);
;                 if (r32 == 0) SS[(size_t)row * 16 + cg] = ss; } });
	v_lshl_add_u64 v[4:5], s[28:29], 0, v[42:43]
	global_load_ushort v46, v[2:3], off
	global_load_ushort v47, v[4:5], off
	ds_read2st64_b32 v[6:7], v34 offset1:1
	ds_read2st64_b32 v[2:3], v34 offset0:32 offset1:33
	ds_read2st64_b32 v[4:5], v34 offset0:48 offset1:49
	ds_read2st64_b32 v[14:15], v34 offset0:16 offset1:17
	ds_read2st64_b32 v[8:9], v34 offset0:64 offset1:65
	ds_read2st64_b32 v[10:11], v34 offset0:96 offset1:97
	ds_read2st64_b32 v[12:13], v34 offset0:112 offset1:113
	ds_read2st64_b32 v[22:23], v34 offset0:80 offset1:81
	ds_read2st64_b32 v[16:17], v34 offset0:128 offset1:129
	s_waitcnt lgkmcnt(8)
	v_add_f32_e32 v6, 0, v6
	s_waitcnt lgkmcnt(7)
	v_add_f32_e32 v2, v6, v2
	ds_read2st64_b32 v[18:19], v34 offset0:160 offset1:161
	ds_read2st64_b32 v[20:21], v34 offset0:176 offset1:177
	ds_read2st64_b32 v[30:31], v34 offset0:144 offset1:145
	ds_read2st64_b32 v[24:25], v34 offset0:192 offset1:193
	s_waitcnt lgkmcnt(8)
	v_add_f32_e32 v2, v2, v8
	s_waitcnt lgkmcnt(7)
	v_add_f32_e32 v2, v2, v10
	s_waitcnt lgkmcnt(4)
	v_add_f32_e32 v2, v2, v16
	s_waitcnt lgkmcnt(3)
	v_add_f32_e32 v2, v2, v18
	s_waitcnt lgkmcnt(0)
	v_add_f32_e32 v6, v2, v24
	v_add_f32_e32 v2, 0, v14
	ds_read2st64_b32 v[26:27], v34 offset0:224 offset1:225
	ds_read2st64_b32 v[28:29], v34 offset0:240 offset1:241
	ds_read2st64_b32 v[34:35], v34 offset0:208 offset1:209
	v_add_f32_e32 v2, v2, v4
	v_add_f32_e32 v2, v2, v22
	v_add_f32_e32 v2, v2, v12
	v_add_f32_e32 v2, v2, v30
	v_add_f32_e32 v2, v2, v20
	s_waitcnt lgkmcnt(0)
	v_add_f32_e32 v4, v2, v34
	v_add_f32_e32 v4, v4, v28
	v_add_f32_e32 v6, v6, v26
	v_cndmask_b32_e32 v2, v212, v36, vcc
	v_lshlrev_b32_e32 v2, 2, v2
	v_cmp_lt_i32_e32 vcc, v38, v37
	v_lshl_add_u64 v[42:43], s[6:7], 0, v[42:43]
	s_waitcnt vmcnt(1)
	v_lshlrev_b32_e32 v8, 16, v46
	s_waitcnt vmcnt(0)
	v_lshlrev_b32_e32 v10, 16, v47
	v_add_f32_e32 v16, v4, v10
	v_add_f32_e32 v12, v6, v8
	v_mul_f32_e32 v6, v16, v16
	v_fmac_f32_e32 v6, v12, v12
	ds_bpermute_b32 v8, v2, v6
	v_cndmask_b32_e32 v4, v212, v38, vcc
	v_lshlrev_b32_e32 v4, 2, v4
	v_cmp_lt_i32_e32 vcc, v39, v37
	s_waitcnt lgkmcnt(0)
	v_add_f32_e32 v8, v6, v8
	ds_bpermute_b32 v10, v4, v8
	v_cndmask_b32_e32 v6, v212, v39, vcc
	v_lshlrev_b32_e32 v6, 2, v6
	v_cmp_lt_i32_e32 vcc, v40, v37
	s_waitcnt lgkmcnt(0)
	v_add_f32_e32 v18, v8, v10
	ds_bpermute_b32 v20, v6, v18
	v_cndmask_b32_e32 v14, v212, v40, vcc
	v_lshlrev_b32_e32 v10, 2, v14
	v_cmp_lt_i32_e32 vcc, v41, v37
	s_waitcnt lgkmcnt(0)
	v_add_f32_e32 v14, v18, v20
	ds_bpermute_b32 v18, v10, v14
	v_bfe_u32 v20, v12, 16, 1
	v_cndmask_b32_e32 v8, v212, v41, vcc
	v_add3_u32 v12, v12, v20, s23
	v_lshlrev_b32_e32 v8, 2, v8
	global_store_short_d16_hi v[44:45], v12, off
	s_waitcnt lgkmcnt(0)
	v_add_f32_e32 v12, v14, v18
	ds_bpermute_b32 v14, v8, v12
	v_bfe_u32 v18, v16, 16, 1
	v_cmp_eq_u32_e32 vcc, 0, v71
	v_add3_u32 v16, v16, v18, s23
	global_store_short_d16_hi v[42:43], v16, off
	s_and_saveexec_b64 s[12:13], vcc
	s_cbranch_execz .LBB0_1321
	v_lshlrev_b64 v[42:43], 6, v[32:33]
	v_lshl_add_u64 v[42:43], s[8:9], 0, v[42:43]
	s_ashr_i32 s11, s10, 31
	s_waitcnt lgkmcnt(0)
	v_add_f32_e32 v12, v12, v14
	v_lshl_add_u64 v[42:43], s[10:11], 2, v[42:43]
	global_store_dword v[42:43], v12, off
